# P2 light pass: next-row cache warm-up loads issued before waiting on the current row
# baseline (speedup 1.0000x reference)
.LBB0_370:
	s_cmp_lt_i32 s36, 3
	s_cselect_b64 s[0:1], -1, 0
	s_cmp_gt_i32 s37, 2
	s_cselect_b64 s[2:3], -1, 0
	s_and_b64 s[0:1], s[0:1], s[2:3]
	s_andn2_b64 vcc, exec, s[0:1]
	s_cbranch_vccnz .LBB0_493
	v_readlane_b32 s4, v254, 2
	v_readlane_b32 s5, v254, 3
	v_mbcnt_lo_u32_b32 v134, -1, 0
	v_mbcnt_hi_u32_b32 v134, -1, v134
	v_lshlrev_b32_e32 v105, 4, v134
	s_load_dwordx2 s[0:1], s[4:5], 0x100
	v_readlane_b32 s2, v254, 0
	s_cmp_gt_i32 s2, 63
	v_readlane_b32 s3, v254, 1
	s_cselect_b32 s6, 32, 0
	s_cmp_ge_i32 s87, s6
	s_mov_b64 s[2:3], -1
	s_cbranch_scc0 .LBB0_406
	s_sub_i32 s2, s87, s6
	s_lshl_b32 s2, s2, 3
	s_add_i32 s2, s2, s94
	s_cmpk_gt_i32 s2, 0x7fff
	s_cbranch_scc1 .LBB0_405
	s_load_dwordx2 s[8:9], s[4:5], 0x38
	s_load_dwordx2 s[12:13], s[4:5], 0x48
	v_lshlrev_b32_e32 v6, 1, v134
	s_waitcnt vmcnt(0)
	v_lshlrev_b32_e32 v4, 2, v134
	v_ashrrev_i32_e32 v7, 31, v6
	v_ashrrev_i32_e32 v5, 31, v4
	s_waitcnt lgkmcnt(0)
	v_lshl_add_u64 v[0:1], v[6:7], 2, s[12:13]
	global_load_dwordx2 v[68:69], v[0:1], off
	v_lshl_add_u64 v[0:1], v[4:5], 2, s[8:9]
	global_load_dwordx4 v[0:3], v[0:1], off
	v_ashrrev_i32_e32 v8, 4, v134
	v_lshlrev_b32_e64 v84, v8, 2
	v_lshlrev_b32_e32 v8, 3, v134
	v_ashrrev_i32_e32 v9, 31, v8
	v_lshlrev_b64 v[8:9], 1, v[8:9]
	v_lshl_add_u64 v[10:11], s[0:1], 0, v[8:9]
	s_mov_b64 s[8:9], 0xd000000
	v_lshl_add_u64 v[70:71], v[10:11], 0, s[8:9]
	v_mbcnt_lo_u32_b32 v10, -1, 0
	v_mbcnt_hi_u32_b32 v10, -1, v10
	v_and_b32_e32 v11, 64, v10
	v_add_u32_e32 v11, 64, v11
	v_xor_b32_e32 v12, 1, v10
	v_cmp_lt_i32_e32 vcc, v12, v11
	v_readlane_b32 s4, v254, 0
	s_sub_i32 s3, s4, s6
	v_cndmask_b32_e32 v12, v10, v12, vcc
	v_lshlrev_b32_e32 v85, 2, v12
	v_xor_b32_e32 v12, 2, v10
	v_cmp_lt_i32_e32 vcc, v12, v11
	v_readlane_b32 s5, v254, 1
	s_lshl_b32 s4, s3, 3
	v_cndmask_b32_e32 v12, v10, v12, vcc
	v_lshlrev_b32_e32 v86, 2, v12
	v_xor_b32_e32 v12, 4, v10
	v_cmp_lt_i32_e32 vcc, v12, v11
	s_lshl_b32 s3, s87, 3
	s_add_i32 s3, s94, s3
	v_cndmask_b32_e32 v12, v10, v12, vcc
	v_lshlrev_b32_e32 v87, 2, v12
	v_xor_b32_e32 v12, 8, v10
	v_cmp_lt_i32_e32 vcc, v12, v11
	s_lshl_b32 s5, s6, 3
	s_sub_i32 s3, s3, s5
	v_cndmask_b32_e32 v12, v10, v12, vcc
	v_lshlrev_b32_e32 v88, 2, v12
	v_xor_b32_e32 v12, 16, v10
	v_cmp_lt_i32_e32 vcc, v12, v11
	s_add_i32 s6, s3, -15
	s_ashr_i32 s3, s2, 31
	v_cndmask_b32_e32 v12, v10, v12, vcc
	v_lshlrev_b32_e32 v89, 2, v12
	v_xor_b32_e32 v12, 32, v10
	v_cmp_lt_i32_e32 vcc, v12, v11
	s_lshl_b64 s[8:9], s[2:3], 8
	s_ashr_i32 s5, s4, 31
	v_cndmask_b32_e32 v10, v10, v12, vcc
	s_lshl_b64 s[12:13], s[2:3], 9
	s_lshl_b64 s[2:3], s[2:3], 10
	v_lshlrev_b32_e32 v90, 2, v10
	v_lshl_add_u64 v[72:73], v[6:7], 1, s[8:9]
	s_lshl_b64 s[8:9], s[4:5], 8
	v_lshl_add_u64 v[74:75], v[4:5], 1, s[12:13]
	s_lshl_b64 s[12:13], s[4:5], 9
	v_lshl_add_u64 v[76:77], s[2:3], 0, v[8:9]
	s_lshl_b64 s[14:15], s[4:5], 10
	s_mov_b32 s5, 0x10a00000
	s_mov_b32 s16, 0xf000000
	v_mov_b32_e32 v91, 0x358637bd
	s_mov_b32 s17, 0x800000
	s_mov_b32 s18, 0x12a00000
	s_brev_b32 s19, 8
	s_branch .LBB0_375
.LBB0_374:
	s_or_b64 exec, exec, s[2:3]
	s_add_i32 s22, s6, s4
	s_ashr_i32 s23, s22, 31
	s_lshl_b64 s[22:23], s[22:23], 10
	s_add_u32 s22, s22, s0
	s_addc_u32 s23, s23, s1
	s_add_u32 s22, s22, 0xd000000
	s_addc_u32 s23, s23, 0
	global_load_dwordx4 v[136:139], v105, s[22:23]
	global_load_dwordx4 v[136:139], v105, s[22:23] offset:1024
	global_load_dwordx4 v[136:139], v105, s[22:23] offset:2048
	global_load_dwordx4 v[136:139], v105, s[22:23] offset:3072
	s_add_u32 s22, s22, 0x1000
	s_addc_u32 s23, s23, 0
	global_load_dwordx4 v[136:139], v105, s[22:23]
	global_load_dwordx4 v[136:139], v105, s[22:23] offset:1024
	global_load_dwordx4 v[136:139], v105, s[22:23] offset:2048
	global_load_dwordx4 v[136:139], v105, s[22:23] offset:3072
	s_add_u32 s22, s22, 0x1000
	s_addc_u32 s23, s23, 0
	global_load_dwordx4 v[136:139], v105, s[22:23]
	global_load_dwordx4 v[136:139], v105, s[22:23] offset:1024
	global_load_dwordx4 v[136:139], v105, s[22:23] offset:2048
	global_load_dwordx4 v[136:139], v105, s[22:23] offset:3072
	s_add_u32 s22, s22, 0x1000
	s_addc_u32 s23, s23, 0
	global_load_dwordx4 v[136:139], v105, s[22:23]
	global_load_dwordx4 v[136:139], v105, s[22:23] offset:1024
	global_load_dwordx4 v[136:139], v105, s[22:23] offset:2048
	global_load_dwordx4 v[136:139], v105, s[22:23] offset:3072
	v_lshl_add_u64 v[140:141], v[100:101], 0, s[8:9]
	global_load_dword v136, v[140:141], off
	s_add_u32 s22, s12, s16
	s_addc_u32 s23, s13, 0
	v_lshl_add_u64 v[142:143], s[0:1], 0, v[74:75]
	v_lshl_add_u64 v[142:143], v[142:143], 0, s[22:23]
	global_load_dwordx2 v[136:137], v[142:143], off
	s_waitcnt vmcnt(18)
	v_lshlrev_b32_e32 v94, 16, v24
	v_and_b32_e32 v95, 0xffff0000, v24
	v_lshlrev_b32_e32 v82, 16, v25
	v_and_b32_e32 v83, 0xffff0000, v25
	v_lshlrev_b32_e32 v80, 16, v26
	v_and_b32_e32 v81, 0xffff0000, v26
	v_lshlrev_b32_e32 v24, 16, v27
	v_and_b32_e32 v25, 0xffff0000, v27
	v_lshlrev_b32_e32 v26, 16, v8
	v_and_b32_e32 v27, 0xffff0000, v8
	v_lshlrev_b32_e32 v8, 16, v9
	v_and_b32_e32 v9, 0xffff0000, v9
	v_lshlrev_b32_e32 v96, 16, v4
	v_and_b32_e32 v97, 0xffff0000, v4
	v_pk_add_f32 v[8:9], v[82:83], v[8:9]
	v_lshlrev_b32_e32 v4, 16, v5
	v_and_b32_e32 v5, 0xffff0000, v5
	v_pk_add_f32 v[4:5], v[8:9], v[4:5]
	v_lshlrev_b32_e32 v8, 16, v21
	v_and_b32_e32 v9, 0xffff0000, v21
	v_pk_add_f32 v[4:5], v[4:5], v[8:9]
	v_lshlrev_b32_e32 v8, 16, v13
	v_and_b32_e32 v9, 0xffff0000, v13
	v_pk_add_f32 v[4:5], v[4:5], v[8:9]
	v_lshlrev_b32_e32 v8, 16, v37
	v_and_b32_e32 v9, 0xffff0000, v37
	v_pk_add_f32 v[26:27], v[94:95], v[26:27]
	v_pk_add_f32 v[4:5], v[4:5], v[8:9]
	v_lshlrev_b32_e32 v8, 16, v29
	v_and_b32_e32 v9, 0xffff0000, v29
	v_pk_add_f32 v[26:27], v[26:27], v[96:97]
	v_lshlrev_b32_e32 v96, 16, v20
	v_and_b32_e32 v97, 0xffff0000, v20
	v_pk_add_f32 v[8:9], v[4:5], v[8:9]
	v_lshlrev_b32_e32 v4, 16, v10
	v_and_b32_e32 v5, 0xffff0000, v10
	v_pk_add_f32 v[26:27], v[26:27], v[96:97]
	v_lshlrev_b32_e32 v96, 16, v12
	v_and_b32_e32 v97, 0xffff0000, v12
	v_pk_add_f32 v[4:5], v[80:81], v[4:5]
	v_lshlrev_b32_e32 v12, 16, v6
	v_and_b32_e32 v13, 0xffff0000, v6
	v_pk_add_f32 v[4:5], v[4:5], v[12:13]
	v_lshlrev_b32_e32 v12, 16, v22
	v_and_b32_e32 v13, 0xffff0000, v22
	v_pk_add_f32 v[4:5], v[4:5], v[12:13]
	v_lshlrev_b32_e32 v12, 16, v14
	v_and_b32_e32 v13, 0xffff0000, v14
	v_pk_add_f32 v[4:5], v[4:5], v[12:13]
	v_lshlrev_b32_e32 v12, 16, v38
	v_and_b32_e32 v13, 0xffff0000, v38
	v_pk_add_f32 v[4:5], v[4:5], v[12:13]
	v_lshlrev_b32_e32 v12, 16, v30
	v_and_b32_e32 v13, 0xffff0000, v30
	v_pk_add_f32 v[12:13], v[4:5], v[12:13]
	v_lshlrev_b32_e32 v4, 16, v11
	v_and_b32_e32 v5, 0xffff0000, v11
	v_pk_add_f32 v[4:5], v[24:25], v[4:5]
	v_lshlrev_b32_e32 v6, 16, v7
	v_and_b32_e32 v7, 0xffff0000, v7
	v_pk_add_f32 v[4:5], v[4:5], v[6:7]
	v_lshlrev_b32_e32 v6, 16, v23
	v_and_b32_e32 v7, 0xffff0000, v23
	v_pk_add_f32 v[4:5], v[4:5], v[6:7]
	v_lshlrev_b32_e32 v6, 16, v15
	v_and_b32_e32 v7, 0xffff0000, v15
	v_lshlrev_b32_e32 v14, 16, v50
	v_and_b32_e32 v15, 0xffff0000, v50
	v_cvt_f32_i32_e32 v50, v92
	v_lshlrev_b32_e32 v20, 16, v51
	v_and_b32_e32 v21, 0xffff0000, v51
	v_pk_add_f32 v[26:27], v[26:27], v[96:97]
	v_div_scale_f32 v51, s[2:3], v50, v50, 1.0
	v_lshlrev_b32_e32 v96, 16, v36
	v_and_b32_e32 v97, 0xffff0000, v36
	v_pk_add_f32 v[4:5], v[4:5], v[6:7]
	v_lshlrev_b32_e32 v6, 16, v39
	v_and_b32_e32 v7, 0xffff0000, v39
	v_lshlrev_b32_e32 v38, 16, v60
	v_and_b32_e32 v39, 0xffff0000, v60
	v_rcp_f32_e32 v60, v51
	v_pk_add_f32 v[26:27], v[26:27], v[96:97]
	v_lshlrev_b32_e32 v96, 16, v28
	v_and_b32_e32 v97, 0xffff0000, v28
	v_pk_add_f32 v[4:5], v[4:5], v[6:7]
	v_lshlrev_b32_e32 v6, 16, v31
	v_and_b32_e32 v7, 0xffff0000, v31
	v_pk_add_f32 v[26:27], v[26:27], v[96:97]
	v_pk_add_f32 v[10:11], v[4:5], v[6:7]
	v_lshlrev_b32_e32 v4, 16, v48
	v_and_b32_e32 v5, 0xffff0000, v48
	v_lshlrev_b32_e32 v6, 16, v49
	v_and_b32_e32 v7, 0xffff0000, v49
	v_lshlrev_b32_e32 v22, 16, v44
	v_and_b32_e32 v23, 0xffff0000, v44
	v_lshlrev_b32_e32 v28, 16, v45
	v_and_b32_e32 v29, 0xffff0000, v45
	v_pk_add_f32 v[4:5], v[26:27], v[4:5]
	v_pk_add_f32 v[6:7], v[8:9], v[6:7]
	v_lshlrev_b32_e32 v44, 16, v61
	v_and_b32_e32 v45, 0xffff0000, v61
	v_fma_f32 v61, -v51, v60, 1.0
	v_pk_add_f32 v[4:5], v[4:5], v[22:23]
	v_pk_add_f32 v[6:7], v[6:7], v[28:29]
	v_fmac_f32_e32 v60, v61, v60
	v_div_scale_f32 v61, vcc, 1.0, v50, 1.0
	v_pk_add_f32 v[4:5], v[4:5], v[38:39]
	v_lshlrev_b32_e32 v22, 16, v16
	v_and_b32_e32 v23, 0xffff0000, v16
	v_pk_add_f32 v[6:7], v[6:7], v[44:45]
	v_lshlrev_b32_e32 v8, 16, v17
	v_and_b32_e32 v9, 0xffff0000, v17
	v_lshlrev_b32_e32 v30, 16, v46
	v_and_b32_e32 v31, 0xffff0000, v46
	v_lshlrev_b32_e32 v36, 16, v47
	v_and_b32_e32 v37, 0xffff0000, v47
	v_lshlrev_b32_e32 v46, 16, v62
	v_and_b32_e32 v47, 0xffff0000, v62
	v_mul_f32_e32 v62, v61, v60
	v_pk_add_f32 v[4:5], v[4:5], v[22:23]
	v_lshlrev_b32_e32 v22, 16, v40
	v_and_b32_e32 v23, 0xffff0000, v40
	v_pk_add_f32 v[6:7], v[6:7], v[8:9]
	v_lshlrev_b32_e32 v8, 16, v41
	v_and_b32_e32 v9, 0xffff0000, v41
	v_lshlrev_b32_e32 v48, 16, v63
	v_and_b32_e32 v49, 0xffff0000, v63
	v_fma_f32 v63, -v51, v62, v61
	v_pk_add_f32 v[4:5], v[4:5], v[22:23]
	v_lshlrev_b32_e32 v22, 16, v32
	v_and_b32_e32 v23, 0xffff0000, v32
	v_pk_add_f32 v[6:7], v[6:7], v[8:9]
	v_lshlrev_b32_e32 v8, 16, v33
	v_and_b32_e32 v9, 0xffff0000, v33
	v_fmac_f32_e32 v62, v63, v60
	v_pk_add_f32 v[4:5], v[4:5], v[22:23]
	v_lshlrev_b32_e32 v22, 16, v56
	v_and_b32_e32 v23, 0xffff0000, v56
	v_pk_add_f32 v[6:7], v[6:7], v[8:9]
	v_lshlrev_b32_e32 v8, 16, v57
	v_and_b32_e32 v9, 0xffff0000, v57
	v_fma_f32 v51, -v51, v62, v61
	v_pk_add_f32 v[4:5], v[4:5], v[22:23]
	v_lshlrev_b32_e32 v22, 16, v52
	v_and_b32_e32 v23, 0xffff0000, v52
	v_pk_add_f32 v[6:7], v[6:7], v[8:9]
	v_lshlrev_b32_e32 v8, 16, v53
	v_and_b32_e32 v9, 0xffff0000, v53
	v_div_fmas_f32 v51, v51, v60, v62
	v_pk_add_f32 v[4:5], v[4:5], v[22:23]
	v_lshlrev_b32_e32 v22, 16, v64
	v_and_b32_e32 v23, 0xffff0000, v64
	v_pk_add_f32 v[6:7], v[6:7], v[8:9]
	v_lshlrev_b32_e32 v8, 16, v65
	v_and_b32_e32 v9, 0xffff0000, v65
	v_div_fixup_f32 v50, v51, v50, 1.0
	v_pk_add_f32 v[4:5], v[4:5], v[22:23]
	v_pk_add_f32 v[6:7], v[6:7], v[8:9]
	v_pk_fma_f32 v[4:5], v[50:51], v[4:5], v[94:95] op_sel_hi:[0,1,1] neg_lo:[0,0,1] neg_hi:[0,0,1]
	v_pk_fma_f32 v[6:7], v[50:51], v[6:7], v[82:83] op_sel_hi:[0,1,1] neg_lo:[0,0,1] neg_hi:[0,0,1]
	v_cvt_pk_bf16_f32 v4, v4, v5
	v_cvt_pk_bf16_f32 v5, v6, v7
	v_pk_add_f32 v[6:7], v[12:13], v[14:15]
	v_lshlrev_b32_e32 v8, 16, v18
	v_pk_add_f32 v[6:7], v[6:7], v[30:31]
	v_and_b32_e32 v9, 0xffff0000, v18
	v_pk_add_f32 v[6:7], v[6:7], v[46:47]
	s_add_i32 s6, s6, s4
	v_pk_add_f32 v[6:7], v[6:7], v[8:9]
	v_lshlrev_b32_e32 v8, 16, v42
	v_and_b32_e32 v9, 0xffff0000, v42
	v_pk_add_f32 v[6:7], v[6:7], v[8:9]
	v_lshlrev_b32_e32 v8, 16, v34
	v_and_b32_e32 v9, 0xffff0000, v34
	v_pk_add_f32 v[6:7], v[6:7], v[8:9]
	v_lshlrev_b32_e32 v8, 16, v58
	v_and_b32_e32 v9, 0xffff0000, v58
	v_pk_add_f32 v[6:7], v[6:7], v[8:9]
	v_lshlrev_b32_e32 v8, 16, v54
	v_and_b32_e32 v9, 0xffff0000, v54
	v_pk_add_f32 v[6:7], v[6:7], v[8:9]
	v_lshlrev_b32_e32 v8, 16, v66
	v_and_b32_e32 v9, 0xffff0000, v66
	v_pk_add_f32 v[6:7], v[6:7], v[8:9]
	v_pk_add_f32 v[8:9], v[10:11], v[20:21]
	v_lshlrev_b32_e32 v10, 16, v19
	v_pk_add_f32 v[8:9], v[8:9], v[36:37]
	v_and_b32_e32 v11, 0xffff0000, v19
	v_pk_add_f32 v[8:9], v[8:9], v[48:49]
	v_pk_fma_f32 v[6:7], v[50:51], v[6:7], v[80:81] op_sel_hi:[0,1,1] neg_lo:[0,0,1] neg_hi:[0,0,1]
	v_pk_add_f32 v[8:9], v[8:9], v[10:11]
	v_lshlrev_b32_e32 v10, 16, v43
	v_and_b32_e32 v11, 0xffff0000, v43
	v_pk_add_f32 v[8:9], v[8:9], v[10:11]
	v_lshlrev_b32_e32 v10, 16, v35
	v_and_b32_e32 v11, 0xffff0000, v35
	v_pk_add_f32 v[8:9], v[8:9], v[10:11]
	v_lshlrev_b32_e32 v10, 16, v59
	v_and_b32_e32 v11, 0xffff0000, v59
	v_pk_add_f32 v[8:9], v[8:9], v[10:11]
	v_lshlrev_b32_e32 v10, 16, v55
	v_and_b32_e32 v11, 0xffff0000, v55
	v_pk_add_f32 v[8:9], v[8:9], v[10:11]
	v_lshlrev_b32_e32 v10, 16, v67
	v_and_b32_e32 v11, 0xffff0000, v67
	v_pk_add_f32 v[8:9], v[8:9], v[10:11]
	v_cvt_pk_bf16_f32 v6, v6, v7
	v_pk_fma_f32 v[8:9], v[50:51], v[8:9], v[24:25] op_sel_hi:[0,1,1] neg_lo:[0,0,1] neg_hi:[0,0,1]
	v_cvt_pk_bf16_f32 v7, v8, v9
	v_add_co_u32_e32 v8, vcc, s5, v78
	s_add_i32 s2, s6, 15
	s_nop 0
	v_addc_co_u32_e32 v9, vcc, 0, v79, vcc
	global_store_dwordx4 v[8:9], v[4:7], off
	s_cmp_lt_i32 s2, 0x8000
	v_lshl_add_u64 v[76:77], v[76:77], 0, s[14:15]
	v_lshl_add_u64 v[4:5], s[0:1], 0, v[74:75]
	v_add_co_u32_e32 v6, vcc, s16, v4
	v_lshl_add_u64 v[74:75], v[74:75], 0, s[12:13]
	s_nop 0
	v_addc_co_u32_e32 v7, vcc, 0, v5, vcc
	v_mov_b32_e32 v6, v102
	v_mov_b32_e32 v7, v103
	v_lshlrev_b32_e32 v106, 16, v104
	v_and_b32_e32 v107, 0xffff0000, v104
	v_and_b32_e32 v9, 0xffff0000, v7
	v_and_b32_e32 v11, 0xffff0000, v6
	v_lshlrev_b32_e32 v8, 16, v7
	v_lshlrev_b32_e32 v10, 16, v6
	v_mov_b32_e32 v12, v11
	v_mov_b32_e32 v13, v9
	v_mov_b32_e32 v6, v10
	v_mov_b32_e32 v7, v8
	v_pk_mul_f32 v[12:13], v[12:13], v[12:13]
	s_nop 0
	v_pk_fma_f32 v[6:7], v[6:7], v[6:7], v[12:13]
	s_nop 0
	v_add_f32_e32 v6, v6, v7
	v_pk_mul_f32 v[108:109], v[106:107], v[106:107]
	s_nop 0
	v_add_f32_e32 v108, v108, v109
	s_nop 0
	v_add_f32_dpp v6, v6, v6 quad_perm:[1,0,3,2] row_mask:0xf bank_mask:0xf
	v_add_f32_dpp v108, v108, v108 quad_perm:[1,0,3,2] row_mask:0xf bank_mask:0xf
	s_nop 0
	v_add_f32_dpp v6, v6, v6 quad_perm:[2,3,0,1] row_mask:0xf bank_mask:0xf
	v_add_f32_dpp v108, v108, v108 quad_perm:[2,3,0,1] row_mask:0xf bank_mask:0xf
	s_nop 0
	v_add_f32_dpp v6, v6, v6 row_half_mirror row_mask:0xf bank_mask:0xf
	v_add_f32_dpp v108, v108, v108 row_half_mirror row_mask:0xf bank_mask:0xf
	s_nop 0
	v_add_f32_dpp v6, v6, v6 row_mirror row_mask:0xf bank_mask:0xf
	v_add_f32_dpp v108, v108, v108 row_mirror row_mask:0xf bank_mask:0xf
	s_nop 0
	v_mov_b32_e32 v7, v6
	v_mov_b32_e32 v109, v108
	s_nop 1
	v_permlane16_swap_b32_e32 v6, v7
	v_permlane16_swap_b32_e32 v108, v109
	v_add_f32_e32 v6, v6, v7
	v_add_f32_e32 v108, v108, v109
	v_mov_b32_e32 v7, v6
	v_mov_b32_e32 v109, v108
	s_nop 1
	v_permlane32_swap_b32_e32 v6, v7
	v_permlane32_swap_b32_e32 v108, v109
	v_add_f32_e32 v6, v6, v7
	v_add_f32_e32 v108, v108, v109
	v_fmamk_f32 v6, v6, 0x3b800000, v91
	v_mul_f32_e32 v7, 0x4b800000, v6
	v_cmp_gt_f32_e32 vcc, s17, v6
	s_nop 1
	v_cndmask_b32_e32 v6, v6, v7, vcc
	v_rsq_f32_e32 v6, v6
	s_nop 0
	v_mul_f32_e32 v7, 0x45800000, v6
	v_cndmask_b32_e32 v6, v6, v7, vcc
	v_pk_mul_f32 v[10:11], v[6:7], v[10:11] op_sel_hi:[0,1]
	v_pk_mul_f32 v[6:7], v[6:7], v[8:9] op_sel_hi:[0,1]
	v_pk_mul_f32 v[10:11], v[0:1], v[10:11]
	v_pk_mul_f32 v[6:7], v[2:3], v[6:7]
	v_add_co_u32_e32 v4, vcc, s18, v4
	v_cvt_pk_bf16_f32 v10, v10, v11
	v_cvt_pk_bf16_f32 v11, v6, v7
	v_addc_co_u32_e32 v5, vcc, 0, v5, vcc
	global_store_dwordx2 v[4:5], v[10:11], off
	v_lshl_add_u64 v[4:5], s[0:1], 0, v[72:73]
	v_lshl_add_u64 v[72:73], v[72:73], 0, s[8:9]
	v_fmamk_f32 v108, v108, 0x3c000000, v91
	v_mul_f32_e32 v109, 0x4b800000, v108
	v_cmp_gt_f32_e32 vcc, s17, v108
	s_nop 1
	v_cndmask_b32_e32 v108, v108, v109, vcc
	v_rsq_f32_e32 v108, v108
	s_nop 0
	v_mul_f32_e32 v109, 0x45800000, v108
	v_cndmask_b32_e32 v108, v108, v109, vcc
	v_pk_mul_f32 v[6:7], v[108:109], v[106:107] op_sel_hi:[0,1]
	v_pk_mul_f32 v[6:7], v[68:69], v[6:7]
	v_add_co_u32_e32 v4, vcc, 0x13a00000, v4
	v_cvt_pk_bf16_f32 v6, v6, v7
	s_nop 0
	v_addc_co_u32_e32 v5, vcc, 0, v5, vcc
	global_store_dword v[4:5], v6, off
	s_cbranch_scc0 .LBB0_405
